# attention: one static priority raise for the second wave half (waves 4-7) for the duration of the phase
# baseline (speedup 1.0000x reference)
.LBB0_668:
	s_andn2_b64 vcc, exec, s[22:23]
	s_cbranch_vccnz .LBB0_696
	s_mov_b64 s[22:23], s[96:97]
	v_mov_b32_e32 v5, v1
	s_load_dwordx2 s[30:31], s[22:23], 0xf8
	s_load_dwordx4 s[40:43], s[22:23], 0x30
	v_readlane_b32 s38, v244, 13
	v_and_b32_e32 v148, 63, v5
	v_readlane_b32 s39, v244, 14
	v_lshlrev_b32_e32 v2, 2, v148
	s_waitcnt lgkmcnt(0)
	s_add_u32 s38, s40, s38
	s_addc_u32 s39, s41, s39
	s_load_dwordx2 s[22:23], s[22:23], 0x40
	global_load_dword v7, v2, s[38:39]
	global_load_dword v10, v2, s[38:39] offset:256
	global_load_dword v11, v2, s[38:39] offset:512
	global_load_dword v12, v2, s[38:39] offset:768
	v_cmp_lt_i32_e32 vcc, v219, v218
	v_cvt_f32_i32_e32 v4, s28
	s_movk_i32 s28, 0x101
	v_cndmask_b32_e32 v2, v217, v219, vcc
	v_cmp_lt_i32_e32 vcc, v220, v218
	v_cmp_gt_i32_e64 s[38:39], s28, v5
	s_movk_i32 s28, 0x80
	v_cndmask_b32_e32 v6, v217, v220, vcc
	v_cmp_lt_i32_e32 vcc, v221, v218
	v_lshlrev_b32_e32 v16, 2, v6
	v_add_u32_e32 v6, 0xffffff80, v5
	v_cndmask_b32_e32 v8, v217, v221, vcc
	v_cmp_lt_i32_e32 vcc, v222, v218
	v_lshlrev_b32_e32 v17, 2, v8
	v_bfe_u32 v8, v5, 4, 2
	v_cndmask_b32_e32 v9, v217, v222, vcc
	v_cmp_lt_i32_e32 vcc, v223, v218
	v_lshlrev_b32_e32 v18, 2, v9
	v_sub_u32_e32 v9, 0x80, v5
	v_cndmask_b32_e32 v13, v217, v223, vcc
	v_cmp_lt_i32_e32 vcc, v224, v218
	v_max_i32_e32 v20, v6, v9
	v_lshlrev_b32_e32 v35, 2, v13
	v_cndmask_b32_e32 v14, v217, v224, vcc
	v_cmp_lt_i32_e32 vcc, s28, v5
	v_and_b32_e32 v151, 15, v5
	v_ashrrev_i32_e32 v150, 4, v5
	v_cndmask_b32_e64 v13, 0, 16, vcc
	v_mul_f32_e32 v19, 0xbe99999a, v4
	v_cmp_gt_u32_e32 vcc, s90, v20
	v_lshlrev_b32_e32 v4, 3, v8
	v_bitop3_b32 v9, v150, v5, 7 bitop3:0x78
	v_lshlrev_b32_e32 v156, 2, v8
	v_bitop3_b32 v157, v8, v5, 15 bitop3:0x78
	v_bitop3_b32 v175, v8, v151, 4 bitop3:0x36
	v_lshl_add_u32 v176, v8, 10, 0
	v_mul_f32_e32 v8, 0x3fb8aa3b, v19
	v_cndmask_b32_e64 v19, 15, 14, vcc
	v_cmp_lt_u32_e32 vcc, 63, v20
	v_lshlrev_b32_e32 v21, 10, v151
	v_lshlrev_b32_e32 v9, 4, v9
	v_min_u32_e32 v23, 8, v20
	v_exp_f32_e32 v24, v8
	v_cndmask_b32_e32 v8, 13, v19, vcc
	v_cmp_gt_u32_e32 vcc, 12, v20
	v_lshlrev_b32_e32 v15, 2, v2
	v_add3_u32 v178, 0, v21, v9
	v_cndmask_b32_e32 v9, 9, v23, vcc
	v_lshlrev_b32_e32 v149, 2, v14
	v_ashrrev_i32_e32 v14, 2, v5
	v_and_b32_e32 v154, -16, v14
	v_cmp_lt_u32_e32 vcc, 45, v20
	v_ashrrev_i32_e32 v155, 31, v154
	s_mov_b64 s[28:29], 0x64f8c10
	v_cndmask_b32_e32 v19, 12, v8, vcc
	v_cmp_gt_u32_e32 vcc, 16, v20
	v_mov_b32_e32 v3, v34
	v_and_b32_e32 v2, 48, v5
	v_cndmask_b32_e32 v21, 10, v9, vcc
	v_lshl_add_u64 v[8:9], v[154:155], 1, s[30:31]
	v_lshl_add_u64 v[158:159], v[8:9], 0, s[28:29]
	v_cmp_lt_u32_e32 vcc, 31, v20
	s_add_u32 s28, s30, 0x6400000
	s_addc_u32 s29, s31, 0
	v_cndmask_b32_e32 v19, 11, v19, vcc
	v_cmp_gt_u32_e32 vcc, 23, v20
	s_add_u32 s2, s42, s2
	s_addc_u32 s3, s43, s3
	v_cndmask_b32_e32 v9, v19, v21, vcc
	v_or_b32_e32 v9, v9, v13
	v_lshlrev_b32_e32 v180, 2, v9
	s_waitcnt vmcnt(4)
	v_lshl_add_u64 v[160:161], s[2:3], 0, v[2:3]
	s_load_dword s24, s[72:73], 0x10
	v_lshl_add_u32 v152, v148, 1, 0
	v_lshlrev_b32_e32 v6, 3, v151
	v_mul_lo_u32 v22, v154, s92
	s_mov_b32 s33, 0
	s_waitcnt vmcnt(2)
	v_mul_f32_e32 v23, v7, v10
	ds_bpermute_b32 v23, v15, v23
	s_waitcnt vmcnt(0)
	v_mul_f32_e32 v25, v11, v12
	ds_bpermute_b32 v15, v15, v25
	s_waitcnt lgkmcnt(0)
	s_lshr_b32 s24, s24, 16
	s_cmp_lg_u32 s24, 0
	v_fmac_f32_e32 v23, v7, v10
	ds_bpermute_b32 v7, v16, v23
	v_fmac_f32_e32 v15, v11, v12
	ds_bpermute_b32 v8, v16, v15
	s_cselect_b64 s[2:3], -1, 0
	s_cmp_lg_u64 s[2:3], 0
	s_waitcnt lgkmcnt(1)
	v_add_f32_e32 v7, v23, v7
	ds_bpermute_b32 v11, v17, v7
	s_waitcnt lgkmcnt(1)
	v_add_f32_e32 v8, v15, v8
	ds_bpermute_b32 v12, v17, v8
	s_addc_u32 s2, s74, 0
	s_lshr_b32 s42, s2, 3
	s_waitcnt lgkmcnt(1)
	v_add_f32_e32 v7, v7, v11
	ds_bpermute_b32 v11, v18, v7
	s_waitcnt lgkmcnt(1)
	v_add_f32_e32 v8, v8, v12
	ds_bpermute_b32 v12, v18, v8
	v_fmamk_f32 v10, v24, 0xbf19999a, v215
	s_mul_i32 s3, s35, s42
	s_waitcnt lgkmcnt(1)
	v_add_f32_e32 v7, v7, v11
	ds_bpermute_b32 v9, v35, v7
	s_waitcnt lgkmcnt(1)
	v_add_f32_e32 v8, v8, v12
	ds_bpermute_b32 v11, v35, v8
	s_add_i32 s43, s37, s3
	s_and_b32 s44, s2, -8
	s_waitcnt lgkmcnt(1)
	v_add_f32_e32 v2, v7, v9
	ds_bpermute_b32 v7, v149, v2
	s_waitcnt lgkmcnt(1)
	v_add_f32_e32 v3, v8, v11
	ds_bpermute_b32 v8, v149, v3
	v_lshl_add_u32 v153, v5, 2, s91
	v_add_u32_e32 v177, 0, v4
	s_waitcnt lgkmcnt(1)
	v_add_f32_e32 v2, v2, v7
	v_mul_f32_e32 v2, 0x3fb8aa3b, v2
	s_waitcnt lgkmcnt(0)
	v_add_f32_e32 v3, v3, v8
	v_mul_f32_e32 v3, 0x3fb8aa3b, v3
	v_exp_f32_e32 v2, v2
	v_exp_f32_e32 v3, v3
	v_sub_f32_e32 v179, 1.0, v10
	v_bfi_b32 v182, -16, v14, v5
	s_lshl_b32 s45, s43, 7
	v_sub_f32_e32 v2, v2, v3
	v_add_f32_e32 v181, v10, v2
	v_mad_i64_i32 v[2:3], s[2:3], v150, s89, 0
	v_lshl_or_b32 v2, v151, 4, v2
	v_lshl_add_u64 v[2:3], s[30:31], 0, v[2:3]
	s_mov_b64 s[2:3], 0x6536800
	s_lshl_b32 s46, s42, 10
	v_lshl_add_u64 v[162:163], v[2:3], 0, s[2:3]
	s_lshl_b32 s47, s43, 5
	s_lshl_b32 s48, s42, 8
	v_subrev_u32_e32 v183, 63, v154
	v_sub_u32_e32 v184, 0, v154
	v_lshlrev_b32_e32 v164, 1, v4
	v_lshlrev_b32_e32 v166, 1, v6
	v_add_u32_e32 v185, v152, v22
	v_mul_u32_u24_e32 v226, 0x120, v148
	v_lshl_add_u32 v226, v154, 1, v226
	v_lshrrev_b32_e32 v227, 2, v148
	v_mul_u32_u24_e32 v227, 0x120, v227
	v_and_b32_e32 v228, 3, v148
	v_lshl_add_u32 v227, v228, 3, v227
	v_cmp_lt_u32_e32 vcc, 0xff, v1
	s_nop 4
	s_cbranch_vccz .Lap_skip
	s_setprio 1
.Lap_skip:
	s_branch .LBB0_671
.LBB0_670:
	s_andn2_b64 vcc, exec, s[2:3]
	s_cbranch_vccz .LBB0_696

.LBB0_699:
	s_setprio 0
	v_readlane_b32 s63, v244, 8
